# mixer C: the readers of each 16-key group's exchanged sums (ds_bpermute) run after the next group's independent arithmetic instead of right behind the issue (3 of 4 exposed LDS round trips per tile hi
# baseline (speedup 1.0000x reference)
.Lcc_noload:
	s_cmp_gt_i32 s13, s12
	s_cbranch_scc1 .Lcc_after
	s_cmp_lg_u32 s15, 0
	s_cbranch_scc1 .Lcc_after
	v_add_u32_e32 v135, s14, v127
	ds_read_b128 v[100:103], v135 offset:16384
	ds_read_b128 v[68:71], v135 offset:16448
	ds_read_b128 v[96:99], v135 offset:18944
	ds_read_b128 v[64:67], v135 offset:19008
	ds_read_b128 v[92:95], v135 offset:21504
	ds_read_b128 v[60:63], v135 offset:21568
	ds_read_b128 v[84:87], v135 offset:24064
	ds_read_b128 v[56:59], v135 offset:24128
	ds_read_b128 v[52:55], v135 offset:26624
	ds_read_b128 v[48:51], v135 offset:26688
	ds_read_b128 v[44:47], v135 offset:29184
	ds_read_b128 v[40:43], v135 offset:29248
	ds_read_b128 v[36:39], v135 offset:31744
	ds_read_b128 v[32:35], v135 offset:31808
	ds_read_b128 v[28:31], v135 offset:34304
	ds_read_b128 v[24:27], v135 offset:34368
	s_lshl_b32 s19, s13, 6
	v_add_u32_e32 v91, s19, v116
	v_cmp_lt_i32_e32 vcc, v91, v72
	s_cmp_lg_u32 s13, 0
	s_waitcnt lgkmcnt(0)
	v_mfma_f32_16x16x32_bf16 v[84:87], v[84:87], v[16:19], 0
	v_mfma_f32_16x16x32_bf16 v[100:103], v[100:103], v[16:19], 0
	v_mfma_f32_16x16x32_bf16 v[68:71], v[68:71], v[20:23], v[100:103]
	v_mfma_f32_16x16x32_bf16 v[56:59], v[56:59], v[20:23], v[84:87]
	v_mfma_f32_16x16x32_bf16 v[92:95], v[92:95], v[16:19], 0
	s_nop 5
	v_mul_f32_e32 v82, 0x3e000000, v68
	v_mul_f32_e64 v84, |v82|, s80
	v_exp_f32_e32 v84, v84
	v_max_f32_e32 v82, 0, v82
	v_mfma_f32_16x16x32_bf16 v[60:63], v[60:63], v[20:23], v[92:95]
	v_add_f32_e32 v84, 1.0, v84
	v_log_f32_e32 v84, v84
	v_mfma_f32_16x16x32_bf16 v[96:99], v[96:99], v[16:19], 0
	v_fmac_f32_e32 v82, 0x3f317218, v84
	v_fma_f32 v68, v68, s70, -v82
	v_cndmask_b32_e32 v92, v241, v68, vcc
	v_sub_f32_e32 v68, 0, v82
	v_add_u32_e32 v82, 1, v91
	v_cndmask_b32_e32 v68, 0, v68, vcc
	v_cmp_lt_i32_e32 vcc, v82, v72
	v_mul_f32_e32 v82, 0x3e000000, v69
	v_mul_f32_e64 v84, |v82|, s80
	v_exp_f32_e32 v84, v84
	v_max_f32_e32 v82, 0, v82
	v_mfma_f32_16x16x32_bf16 v[64:67], v[64:67], v[20:23], v[96:99]
	v_add_f32_e32 v84, 1.0, v84
	v_log_f32_e32 v84, v84
	s_nop 0
	v_fmac_f32_e32 v82, 0x3f317218, v84
	v_fma_f32 v69, v69, s70, -v82
	v_cndmask_b32_e32 v98, v241, v69, vcc
	v_add_u32_e32 v69, 2, v91
	v_cndmask_b32_e64 v97, 0, -v82, vcc
	v_cmp_lt_i32_e32 vcc, v69, v72
	v_mul_f32_e32 v69, 0x3e000000, v70
	v_mul_f32_e64 v82, |v69|, s80
	v_exp_f32_e32 v82, v82
	v_max_f32_e32 v69, 0, v69
	v_add_f32_e32 v68, v97, v68
	v_add_f32_e32 v82, 1.0, v82
	v_log_f32_e32 v82, v82
	s_nop 0
	v_fmac_f32_e32 v69, 0x3f317218, v82
	v_cndmask_b32_e64 v99, 0, -v69, vcc
	v_fma_f32 v69, v70, s70, -v69
	v_cndmask_b32_e32 v100, v241, v69, vcc
	v_add_u32_e32 v69, 3, v91
	v_cmp_lt_i32_e32 vcc, v69, v72
	v_mul_f32_e32 v69, 0x3e000000, v71
	v_mul_f32_e64 v70, |v69|, s80
	v_exp_f32_e32 v70, v70
	v_max_f32_e32 v69, 0, v69
	v_add_f32_e32 v68, v99, v68
	v_add_f32_e32 v70, 1.0, v70
	v_log_f32_e32 v70, v70
	s_nop 0
	v_fmac_f32_e32 v69, 0x3f317218, v70
	v_cndmask_b32_e64 v101, 0, -v69, vcc
	v_fma_f32 v69, v71, s70, -v69
	v_cndmask_b32_e32 v102, v241, v69, vcc
	v_add_u32_e32 v69, 16, v91
	v_cmp_lt_i32_e32 vcc, v69, v72
	v_mul_f32_e32 v69, 0x3e000000, v64
	v_mul_f32_e64 v71, |v69|, s80
	v_exp_f32_e32 v71, v71
	v_max_f32_e32 v69, 0, v69
	v_add_f32_e32 v93, v101, v68
	ds_bpermute_b32 v94, v88, v93
	v_add_f32_e32 v71, 1.0, v71
	v_log_f32_e32 v71, v71
	ds_bpermute_b32 v95, v89, v93
	ds_bpermute_b32 v96, v90, v93
	v_fmac_f32_e32 v69, 0x3f317218, v71
	v_fma_f32 v64, v64, s70, -v69
	v_cndmask_b32_e32 v103, v241, v64, vcc
	v_sub_f32_e32 v64, 0, v69
	v_add_u32_e32 v69, 17, v91
	v_cndmask_b32_e32 v64, 0, v64, vcc
	v_cmp_lt_i32_e32 vcc, v69, v72
	v_mul_f32_e32 v69, 0x3e000000, v65
	v_mul_f32_e64 v71, |v69|, s80
	v_exp_f32_e32 v71, v71
	v_max_f32_e32 v69, 0, v69
	v_add_f32_e32 v71, 1.0, v71
	v_log_f32_e32 v71, v71
	s_nop 0
	v_fmac_f32_e32 v69, 0x3f317218, v71
	v_fma_f32 v65, v65, s70, -v69
	v_cndmask_b32_e32 v105, v241, v65, vcc
	v_add_u32_e32 v65, 18, v91
	v_cndmask_b32_e64 v104, 0, -v69, vcc
	v_cmp_lt_i32_e32 vcc, v65, v72
	v_mul_f32_e32 v65, 0x3e000000, v66
	v_mul_f32_e64 v69, |v65|, s80
	v_exp_f32_e32 v69, v69
	v_max_f32_e32 v65, 0, v65
	v_add_f32_e32 v64, v104, v64
	v_add_f32_e32 v69, 1.0, v69
	v_log_f32_e32 v69, v69
	s_nop 0
	v_fmac_f32_e32 v65, 0x3f317218, v69
	v_cndmask_b32_e64 v106, 0, -v65, vcc
	v_fma_f32 v65, v66, s70, -v65
	v_cndmask_b32_e32 v107, v241, v65, vcc
	v_add_u32_e32 v65, 19, v91
	v_cmp_lt_i32_e32 vcc, v65, v72
	v_mul_f32_e32 v65, 0x3e000000, v67
	v_mul_f32_e64 v66, |v65|, s80
	v_exp_f32_e32 v66, v66
	v_max_f32_e32 v65, 0, v65
	v_add_f32_e32 v64, v106, v64
	v_add_f32_e32 v66, 1.0, v66
	v_log_f32_e32 v66, v66
	s_nop 0
	v_fmac_f32_e32 v65, 0x3f317218, v66
	v_cndmask_b32_e64 v108, 0, -v65, vcc
	v_fma_f32 v65, v67, s70, -v65
	v_add_f32_e32 v64, v108, v64
	v_cndmask_b32_e32 v109, v241, v65, vcc
	s_waitcnt lgkmcnt(0)
	v_cndmask_b32_e64 v70, 0, v94, s[6:7]
	v_cndmask_b32_e64 v84, 0, v95, s[8:9]
	v_cndmask_b32_e64 v68, 0, v96, s[10:11]
	ds_bpermute_b32 v208, v88, v64
	ds_bpermute_b32 v209, v89, v64
	ds_bpermute_b32 v85, v90, v64
	v_add_u32_e32 v65, 32, v91
	v_cmp_lt_i32_e32 vcc, v65, v72
	v_mul_f32_e32 v65, 0x3e000000, v60
	v_mul_f32_e64 v67, |v65|, s80
	v_exp_f32_e32 v67, v67
	v_max_f32_e32 v65, 0, v65
	v_add_f32_e32 v67, 1.0, v67
	v_log_f32_e32 v67, v67
	s_nop 0
	v_fmac_f32_e32 v65, 0x3f317218, v67
	v_fma_f32 v60, v60, s70, -v65
	v_cndmask_b32_e32 v110, v241, v60, vcc
	v_sub_f32_e32 v60, 0, v65
	v_add_u32_e32 v65, 33, v91
	v_cndmask_b32_e32 v60, 0, v60, vcc
	v_cmp_lt_i32_e32 vcc, v65, v72
	v_mul_f32_e32 v65, 0x3e000000, v61
	v_mul_f32_e64 v67, |v65|, s80
	v_exp_f32_e32 v67, v67
	v_max_f32_e32 v65, 0, v65
	v_add_f32_e32 v67, 1.0, v67
	v_log_f32_e32 v67, v67
	s_nop 0
	v_fmac_f32_e32 v65, 0x3f317218, v67
	v_fma_f32 v61, v61, s70, -v65
	v_cndmask_b32_e32 v112, v241, v61, vcc
	v_add_u32_e32 v61, 34, v91
	v_cndmask_b32_e64 v111, 0, -v65, vcc
	v_cmp_lt_i32_e32 vcc, v61, v72
	v_mul_f32_e32 v61, 0x3e000000, v62
	v_mul_f32_e64 v65, |v61|, s80
	v_exp_f32_e32 v65, v65
	v_max_f32_e32 v61, 0, v61
	v_add_f32_e32 v60, v111, v60
	v_add_f32_e32 v65, 1.0, v65
	v_log_f32_e32 v65, v65
	s_nop 0
	v_fmac_f32_e32 v61, 0x3f317218, v65
	v_cndmask_b32_e64 v113, 0, -v61, vcc
	v_fma_f32 v61, v62, s70, -v61
	v_cndmask_b32_e32 v114, v241, v61, vcc
	v_add_u32_e32 v61, 35, v91
	v_cmp_lt_i32_e32 vcc, v61, v72
	v_mul_f32_e32 v61, 0x3e000000, v63
	v_mul_f32_e64 v62, |v61|, s80
	v_exp_f32_e32 v62, v62
	v_max_f32_e32 v61, 0, v61
	v_add_f32_e32 v60, v113, v60
	v_add_f32_e32 v62, 1.0, v62
	v_log_f32_e32 v62, v62
	s_nop 0
	v_fmac_f32_e32 v61, 0x3f317218, v62
	v_cndmask_b32_e64 v117, 0, -v61, vcc
	v_fma_f32 v61, v63, s70, -v61
	v_add_f32_e32 v60, v117, v60
	v_cndmask_b32_e32 v118, v241, v61, vcc
	s_waitcnt lgkmcnt(0)
	v_add_f32_e32 v64, v64, v208
	v_cndmask_b32_e64 v66, 0, v208, s[6:7]
	v_add_f32_e32 v71, v64, v209
	v_cndmask_b32_e64 v86, 0, v209, s[8:9]
	v_cndmask_b32_e64 v64, 0, v85, s[10:11]
	ds_bpermute_b32 v211, v88, v60
	ds_bpermute_b32 v212, v89, v60
	ds_bpermute_b32 v87, v90, v60
	v_add_u32_e32 v61, 48, v91
	v_cmp_lt_i32_e32 vcc, v61, v72
	v_mul_f32_e32 v61, 0x3e000000, v56
	v_mul_f32_e64 v63, |v61|, s80
	v_exp_f32_e32 v63, v63
	v_max_f32_e32 v61, 0, v61
	v_add_f32_e32 v63, 1.0, v63
	v_log_f32_e32 v63, v63
	s_nop 0
	v_fmac_f32_e32 v61, 0x3f317218, v63
	v_fma_f32 v56, v56, s70, -v61
	v_cndmask_b32_e32 v119, v241, v56, vcc
	v_sub_f32_e32 v56, 0, v61
	v_add_u32_e32 v61, 49, v91
	v_cndmask_b32_e32 v56, 0, v56, vcc
	v_cmp_lt_i32_e32 vcc, v61, v72
	v_mul_f32_e32 v61, 0x3e000000, v57
	v_mul_f32_e64 v63, |v61|, s80
	v_exp_f32_e32 v63, v63
	v_max_f32_e32 v61, 0, v61
	v_add_f32_e32 v63, 1.0, v63
	v_log_f32_e32 v63, v63
	s_nop 0
	v_fmac_f32_e32 v61, 0x3f317218, v63
	v_fma_f32 v57, v57, s70, -v61
	v_cndmask_b32_e32 v121, v241, v57, vcc
	v_add_u32_e32 v57, 50, v91
	v_cndmask_b32_e64 v120, 0, -v61, vcc
	v_cmp_lt_i32_e32 vcc, v57, v72
	v_mul_f32_e32 v57, 0x3e000000, v58
	v_mul_f32_e64 v61, |v57|, s80
	v_exp_f32_e32 v61, v61
	v_max_f32_e32 v57, 0, v57
	v_add_f32_e32 v56, v120, v56
	v_add_f32_e32 v61, 1.0, v61
	v_log_f32_e32 v61, v61
	s_nop 0
	v_fmac_f32_e32 v57, 0x3f317218, v61
	v_cndmask_b32_e64 v122, 0, -v57, vcc
	v_fma_f32 v57, v58, s70, -v57
	v_cndmask_b32_e32 v123, v241, v57, vcc
	v_add_u32_e32 v57, 51, v91
	v_cmp_lt_i32_e32 vcc, v57, v72
	v_mul_f32_e32 v57, 0x3e000000, v59
	v_mul_f32_e64 v58, |v57|, s80
	v_exp_f32_e32 v58, v58
	v_max_f32_e32 v57, 0, v57
	v_add_f32_e32 v56, v122, v56
	v_add_f32_e32 v58, 1.0, v58
	v_log_f32_e32 v58, v58
	s_nop 0
	v_fmac_f32_e32 v57, 0x3f317218, v58
	v_cndmask_b32_e64 v124, 0, -v57, vcc
	v_fma_f32 v57, v59, s70, -v57
	v_add_f32_e32 v56, v124, v56
	v_cndmask_b32_e32 v125, v241, v57, vcc
	s_waitcnt lgkmcnt(0)
	v_add_f32_e32 v60, v60, v211
	v_add_f32_e32 v67, v60, v212
	v_cndmask_b32_e64 v60, 0, v211, s[6:7]
	v_cndmask_b32_e64 v62, 0, v212, s[8:9]
	v_cndmask_b32_e64 v82, 0, v87, s[10:11]
	ds_bpermute_b32 v57, v88, v56
	ds_bpermute_b32 v58, v89, v56
	ds_bpermute_b32 v63, v90, v56
	s_waitcnt lgkmcnt(2)
	v_add_f32_e32 v56, v56, v57
	s_waitcnt lgkmcnt(1)
	v_add_f32_e32 v61, v56, v58
	v_cndmask_b32_e64 v56, 0, v57, s[6:7]
	v_cndmask_b32_e64 v57, 0, v58, s[8:9]
	v_add_f32_e32 v56, v56, v57
	s_waitcnt lgkmcnt(0)
	v_cndmask_b32_e64 v57, 0, v63, s[10:11]
	v_add_f32_e32 v56, v56, v57
	v_add_f32_e32 v126, v83, v56
	v_pk_add_f32 v[56:57], v[60:61], v[62:63]
	v_pk_add_f32 v[58:59], v[66:67], v[86:87]
	v_pk_add_f32 v[60:61], v[56:57], v[82:83]
	v_add_f32_e32 v82, v124, v126
	v_mov_b32_e32 v65, v61
	v_pk_add_f32 v[62:63], v[58:59], v[64:65]
	v_add_f32_e32 v56, v60, v61
	v_pk_add_f32 v[60:61], v[70:71], v[84:85]
	v_mov_b32_e32 v69, v63
	v_add_f32_e32 v58, v62, v63
	v_pk_add_f32 v[62:63], v[60:61], v[68:69]
	v_add_f32_e32 v65, v109, v58
	v_add_f32_e32 v60, v62, v63
	v_add_f32_e32 v62, v102, v60
	v_mul_f32_e32 v62, 0x3fb8aa3b, v62
	v_add_f32_e32 v60, v101, v60
	v_exp_f32_e32 v63, v62
	v_add_f32_e32 v62, v100, v60
	v_add_f32_e32 v58, v108, v58
	v_mul_f32_e32 v62, 0x3fb8aa3b, v62
	v_add_f32_e32 v60, v99, v60
	v_add_f32_e32 v66, v107, v58
	v_add_f32_e32 v58, v106, v58
	v_exp_f32_e32 v64, v62
	v_add_f32_e32 v62, v98, v60
	v_add_f32_e32 v60, v97, v60
	v_add_f32_e32 v67, v105, v58
	v_add_f32_e32 v58, v104, v58
	v_add_f32_e32 v60, v92, v60
	v_add_f32_e32 v58, v103, v58
	v_mul_f32_e32 v62, 0x3fb8aa3b, v62
	v_mul_f32_e32 v60, 0x3fb8aa3b, v60
	v_mul_f32_e32 v65, 0x3fb8aa3b, v65
	v_mul_f32_e32 v66, 0x3fb8aa3b, v66
	v_mul_f32_e32 v67, 0x3fb8aa3b, v67
	v_mul_f32_e32 v58, 0x3fb8aa3b, v58
	v_add_f32_e32 v68, v118, v56
	v_add_f32_e32 v56, v117, v56
	v_exp_f32_e32 v62, v62
	v_exp_f32_e32 v60, v60
	v_exp_f32_e32 v65, v65
	v_exp_f32_e32 v66, v66
	v_exp_f32_e32 v67, v67
	v_exp_f32_e32 v58, v58
	v_add_f32_e32 v69, v114, v56
	v_add_f32_e32 v56, v113, v56
	v_add_f32_e32 v84, v123, v82
	v_add_f32_e32 v82, v122, v82
	v_add_f32_e32 v70, v112, v56
	v_add_f32_e32 v56, v111, v56
	v_add_f32_e32 v85, v121, v82
	v_add_f32_e32 v82, v120, v82
	v_add_f32_e32 v56, v110, v56
	v_add_f32_e32 v71, v125, v126
	v_add_f32_e32 v82, v119, v82
	v_mul_f32_e32 v68, 0x3fb8aa3b, v68
	v_mul_f32_e32 v69, 0x3fb8aa3b, v69
	v_mul_f32_e32 v70, 0x3fb8aa3b, v70
	v_mul_f32_e32 v56, 0x3fb8aa3b, v56
	v_mul_f32_e32 v71, 0x3fb8aa3b, v71
	v_mul_f32_e32 v84, 0x3fb8aa3b, v84
	v_mul_f32_e32 v85, 0x3fb8aa3b, v85
	v_mul_f32_e32 v82, 0x3fb8aa3b, v82
	v_exp_f32_e32 v68, v68
	v_exp_f32_e32 v69, v69
	v_exp_f32_e32 v70, v70
	v_exp_f32_e32 v56, v56
	v_exp_f32_e32 v71, v71
	v_exp_f32_e32 v84, v84
	v_exp_f32_e32 v85, v85
	v_exp_f32_e32 v82, v82
	v_cvt_pk_bf16_f32 v62, v60, v62
	v_cvt_pk_bf16_f32 v63, v64, v63
	v_cvt_pk_bf16_f32 v64, v58, v67
	v_cvt_pk_bf16_f32 v65, v66, v65
	v_cvt_pk_bf16_f32 v66, v56, v70
	v_cvt_pk_bf16_f32 v67, v69, v68
	v_mfma_f32_16x16x32_bf16 v[0:3], v[52:55], v[62:65], v[0:3]
	v_cvt_pk_bf16_f32 v68, v82, v85
	v_cvt_pk_bf16_f32 v69, v84, v71
	v_mfma_f32_16x16x32_bf16 v[4:7], v[44:47], v[62:65], v[4:7]
	v_mfma_f32_16x16x32_bf16 v[8:11], v[36:39], v[62:65], v[8:11]
	v_mfma_f32_16x16x32_bf16 v[12:15], v[28:31], v[62:65], v[12:15]
	v_mfma_f32_16x16x32_bf16 v[0:3], v[48:51], v[66:69], v[0:3]
	v_mfma_f32_16x16x32_bf16 v[4:7], v[40:43], v[66:69], v[4:7]
	v_mfma_f32_16x16x32_bf16 v[8:11], v[32:35], v[66:69], v[8:11]
	v_mfma_f32_16x16x32_bf16 v[12:15], v[24:27], v[66:69], v[12:15]
	s_cbranch_scc0 .Lcc_last
	v_add_f32_e32 v24, v93, v94
	v_add_f32_e32 v24, v24, v95
	v_add_f32_e32 v24, v24, v96
	v_add_f32_e32 v24, v24, v61
	v_add_f32_e32 v24, v24, v59
	v_add_f32_e32 v24, v24, v57
	v_add_f32_e32 v83, v83, v24
	v_cmp_lt_f32_e32 vcc, s38, v83
	s_cbranch_vccnz .Lcc_after
